# v17: P5 SwiGLU epilogue rewritten: h = a*b*rcp(fma(exp2(a*(-rs*log2e)), 1/rs^2, 1/rs^2)); no register shuffles, 32-bit saddr stores
# speedup vs baseline: 1.0268x; 1.0017x over previous
.LBB0_1561:
	v_lshl_add_u32 v146, s22, 8, v150
	v_ashrrev_i32_e32 v147, 31, v146
	v_lshl_add_u64 v[148:149], v[146:147], 2, s[8:9]
	global_load_dword v188, v[148:149], off
	global_load_dword v190, v[148:149], off offset:64
	global_load_dword v192, v[148:149], off offset:128
	global_load_dword v194, v[148:149], off offset:192
	global_load_dword v196, v[148:149], off offset:512
	global_load_dword v198, v[148:149], off offset:576
	global_load_dword v200, v[148:149], off offset:640
	global_load_dword v202, v[148:149], off offset:704
	s_andn2_b64 vcc, exec, s[2:3]
	s_mov_b64 s[2:3], -1
	v_lshl_or_b32 v158, s50, 7, v152
	v_mul_u32_u24_e32 v175, 0x1600, v146
	v_lshl_add_u32 v175, v158, 1, v175
	s_mov_b32 s26, s6
	s_mov_b32 s27, s7
	s_waitcnt vmcnt(7)
	v_mul_f32_e32 v172, 0xbfb8aa3b, v188
	v_mul_f32_e32 v173, v188, v188
	v_rcp_f32_e32 v174, v173
	v_mul_f32_e32 v156, v172, v122
	v_mul_f32_e32 v157, v172, v123
	v_mul_f32_e32 v158, v172, v124
	v_mul_f32_e32 v159, v172, v125
	v_mul_f32_e32 v160, v172, v114
	v_mul_f32_e32 v161, v172, v115
	v_mul_f32_e32 v162, v172, v116
	v_mul_f32_e32 v163, v172, v117
	v_exp_f32_e32 v156, v156
	v_exp_f32_e32 v157, v157
	v_exp_f32_e32 v158, v158
	v_exp_f32_e32 v159, v159
	v_exp_f32_e32 v160, v160
	v_exp_f32_e32 v161, v161
	v_exp_f32_e32 v162, v162
	v_exp_f32_e32 v163, v163
	v_mul_f32_e32 v126, v122, v126
	v_mul_f32_e32 v127, v123, v127
	v_mul_f32_e32 v128, v124, v128
	v_mul_f32_e32 v129, v125, v129
	v_mul_f32_e32 v118, v114, v118
	v_mul_f32_e32 v119, v115, v119
	v_mul_f32_e32 v120, v116, v120
	v_mul_f32_e32 v121, v117, v121
	v_fma_f32 v156, v156, v174, v174
	v_fma_f32 v157, v157, v174, v174
	v_fma_f32 v158, v158, v174, v174
	v_fma_f32 v159, v159, v174, v174
	v_fma_f32 v160, v160, v174, v174
	v_fma_f32 v161, v161, v174, v174
	v_fma_f32 v162, v162, v174, v174
	v_fma_f32 v163, v163, v174, v174
	v_rcp_f32_e32 v156, v156
	v_rcp_f32_e32 v157, v157
	v_rcp_f32_e32 v158, v158
	v_rcp_f32_e32 v159, v159
	v_rcp_f32_e32 v160, v160
	v_rcp_f32_e32 v161, v161
	v_rcp_f32_e32 v162, v162
	v_rcp_f32_e32 v163, v163
	s_nop 0
	v_mul_f32_e32 v126, v126, v156
	v_mul_f32_e32 v127, v127, v157
	v_mul_f32_e32 v128, v128, v158
	v_mul_f32_e32 v129, v129, v159
	v_mul_f32_e32 v118, v118, v160
	v_mul_f32_e32 v119, v119, v161
	v_mul_f32_e32 v120, v120, v162
	v_mul_f32_e32 v121, v121, v163
	v_cvt_pk_bf16_f32 v122, v126, v127
	v_cvt_pk_bf16_f32 v123, v128, v129
	v_cvt_pk_bf16_f32 v124, v118, v119
	v_cvt_pk_bf16_f32 v125, v120, v121
	global_store_dwordx4 v175, v[122:125], s[26:27]
	s_waitcnt vmcnt(7)
	v_mul_f32_e32 v172, 0xbfb8aa3b, v190
	v_mul_f32_e32 v173, v190, v190
	v_rcp_f32_e32 v174, v173
	v_mul_f32_e32 v164, v172, v106
	v_mul_f32_e32 v165, v172, v107
	v_mul_f32_e32 v166, v172, v108
	v_mul_f32_e32 v167, v172, v109
	v_mul_f32_e32 v168, v172, v98
	v_mul_f32_e32 v169, v172, v99
	v_mul_f32_e32 v170, v172, v100
	v_mul_f32_e32 v171, v172, v101
	v_exp_f32_e32 v164, v164
	v_exp_f32_e32 v165, v165
	v_exp_f32_e32 v166, v166
	v_exp_f32_e32 v167, v167
	v_exp_f32_e32 v168, v168
	v_exp_f32_e32 v169, v169
	v_exp_f32_e32 v170, v170
	v_exp_f32_e32 v171, v171
	v_mul_f32_e32 v110, v106, v110
	v_mul_f32_e32 v111, v107, v111
	v_mul_f32_e32 v112, v108, v112
	v_mul_f32_e32 v113, v109, v113
	v_mul_f32_e32 v102, v98, v102
	v_mul_f32_e32 v103, v99, v103
	v_mul_f32_e32 v104, v100, v104
	v_mul_f32_e32 v105, v101, v105
	v_fma_f32 v164, v164, v174, v174
	v_fma_f32 v165, v165, v174, v174
	v_fma_f32 v166, v166, v174, v174
	v_fma_f32 v167, v167, v174, v174
	v_fma_f32 v168, v168, v174, v174
	v_fma_f32 v169, v169, v174, v174
	v_fma_f32 v170, v170, v174, v174
	v_fma_f32 v171, v171, v174, v174
	v_rcp_f32_e32 v164, v164
	v_rcp_f32_e32 v165, v165
	v_rcp_f32_e32 v166, v166
	v_rcp_f32_e32 v167, v167
	v_rcp_f32_e32 v168, v168
	v_rcp_f32_e32 v169, v169
	v_rcp_f32_e32 v170, v170
	v_rcp_f32_e32 v171, v171
	s_add_u32 s26, s26, 0x16000
	s_addc_u32 s27, s27, 0
	v_mul_f32_e32 v110, v110, v164
	v_mul_f32_e32 v111, v111, v165
	v_mul_f32_e32 v112, v112, v166
	v_mul_f32_e32 v113, v113, v167
	v_mul_f32_e32 v102, v102, v168
	v_mul_f32_e32 v103, v103, v169
	v_mul_f32_e32 v104, v104, v170
	v_mul_f32_e32 v105, v105, v171
	v_cvt_pk_bf16_f32 v106, v110, v111
	v_cvt_pk_bf16_f32 v107, v112, v113
	v_cvt_pk_bf16_f32 v108, v102, v103
	v_cvt_pk_bf16_f32 v109, v104, v105
	global_store_dwordx4 v175, v[106:109], s[26:27]
	s_waitcnt vmcnt(7)
	v_mul_f32_e32 v172, 0xbfb8aa3b, v192
	v_mul_f32_e32 v173, v192, v192
	v_rcp_f32_e32 v174, v173
	v_mul_f32_e32 v156, v172, v90
	v_mul_f32_e32 v157, v172, v91
	v_mul_f32_e32 v158, v172, v92
	v_mul_f32_e32 v159, v172, v93
	v_mul_f32_e32 v160, v172, v82
	v_mul_f32_e32 v161, v172, v83
	v_mul_f32_e32 v162, v172, v84
	v_mul_f32_e32 v163, v172, v85
	v_exp_f32_e32 v156, v156
	v_exp_f32_e32 v157, v157
	v_exp_f32_e32 v158, v158
	v_exp_f32_e32 v159, v159
	v_exp_f32_e32 v160, v160
	v_exp_f32_e32 v161, v161
	v_exp_f32_e32 v162, v162
	v_exp_f32_e32 v163, v163
	v_mul_f32_e32 v94, v90, v94
	v_mul_f32_e32 v95, v91, v95
	v_mul_f32_e32 v96, v92, v96
	v_mul_f32_e32 v97, v93, v97
	v_mul_f32_e32 v86, v82, v86
	v_mul_f32_e32 v87, v83, v87
	v_mul_f32_e32 v88, v84, v88
	v_mul_f32_e32 v89, v85, v89
	v_fma_f32 v156, v156, v174, v174
	v_fma_f32 v157, v157, v174, v174
	v_fma_f32 v158, v158, v174, v174
	v_fma_f32 v159, v159, v174, v174
	v_fma_f32 v160, v160, v174, v174
	v_fma_f32 v161, v161, v174, v174
	v_fma_f32 v162, v162, v174, v174
	v_fma_f32 v163, v163, v174, v174
	v_rcp_f32_e32 v156, v156
	v_rcp_f32_e32 v157, v157
	v_rcp_f32_e32 v158, v158
	v_rcp_f32_e32 v159, v159
	v_rcp_f32_e32 v160, v160
	v_rcp_f32_e32 v161, v161
	v_rcp_f32_e32 v162, v162
	v_rcp_f32_e32 v163, v163
	s_add_u32 s26, s26, 0x16000
	s_addc_u32 s27, s27, 0
	v_mul_f32_e32 v94, v94, v156
	v_mul_f32_e32 v95, v95, v157
	v_mul_f32_e32 v96, v96, v158
	v_mul_f32_e32 v97, v97, v159
	v_mul_f32_e32 v86, v86, v160
	v_mul_f32_e32 v87, v87, v161
	v_mul_f32_e32 v88, v88, v162
	v_mul_f32_e32 v89, v89, v163
	v_cvt_pk_bf16_f32 v90, v94, v95
	v_cvt_pk_bf16_f32 v91, v96, v97
	v_cvt_pk_bf16_f32 v92, v86, v87
	v_cvt_pk_bf16_f32 v93, v88, v89
	global_store_dwordx4 v175, v[90:93], s[26:27]
	s_waitcnt vmcnt(7)
	v_mul_f32_e32 v172, 0xbfb8aa3b, v194
	v_mul_f32_e32 v173, v194, v194
	v_rcp_f32_e32 v174, v173
	v_mul_f32_e32 v164, v172, v74
	v_mul_f32_e32 v165, v172, v75
	v_mul_f32_e32 v166, v172, v76
	v_mul_f32_e32 v167, v172, v77
	v_mul_f32_e32 v168, v172, v70
	v_mul_f32_e32 v169, v172, v71
	v_mul_f32_e32 v170, v172, v72
	v_mul_f32_e32 v171, v172, v73
	v_exp_f32_e32 v164, v164
	v_exp_f32_e32 v165, v165
	v_exp_f32_e32 v166, v166
	v_exp_f32_e32 v167, v167
	v_exp_f32_e32 v168, v168
	v_exp_f32_e32 v169, v169
	v_exp_f32_e32 v170, v170
	v_exp_f32_e32 v171, v171
	v_mul_f32_e32 v78, v74, v78
	v_mul_f32_e32 v79, v75, v79
	v_mul_f32_e32 v80, v76, v80
	v_mul_f32_e32 v81, v77, v81
	v_mul_f32_e32 v66, v70, v66
	v_mul_f32_e32 v67, v71, v67
	v_mul_f32_e32 v68, v72, v68
	v_mul_f32_e32 v69, v73, v69
	v_fma_f32 v164, v164, v174, v174
	v_fma_f32 v165, v165, v174, v174
	v_fma_f32 v166, v166, v174, v174
	v_fma_f32 v167, v167, v174, v174
	v_fma_f32 v168, v168, v174, v174
	v_fma_f32 v169, v169, v174, v174
	v_fma_f32 v170, v170, v174, v174
	v_fma_f32 v171, v171, v174, v174
	v_rcp_f32_e32 v164, v164
	v_rcp_f32_e32 v165, v165
	v_rcp_f32_e32 v166, v166
	v_rcp_f32_e32 v167, v167
	v_rcp_f32_e32 v168, v168
	v_rcp_f32_e32 v169, v169
	v_rcp_f32_e32 v170, v170
	v_rcp_f32_e32 v171, v171
	s_add_u32 s26, s26, 0x16000
	s_addc_u32 s27, s27, 0
	v_mul_f32_e32 v78, v78, v164
	v_mul_f32_e32 v79, v79, v165
	v_mul_f32_e32 v80, v80, v166
	v_mul_f32_e32 v81, v81, v167
	v_mul_f32_e32 v66, v66, v168
	v_mul_f32_e32 v67, v67, v169
	v_mul_f32_e32 v68, v68, v170
	v_mul_f32_e32 v69, v69, v171
	v_cvt_pk_bf16_f32 v74, v78, v79
	v_cvt_pk_bf16_f32 v75, v80, v81
	v_cvt_pk_bf16_f32 v76, v66, v67
	v_cvt_pk_bf16_f32 v77, v68, v69
	global_store_dwordx4 v175, v[74:77], s[26:27]
	s_waitcnt vmcnt(7)
	v_mul_f32_e32 v172, 0xbfb8aa3b, v196
	v_mul_f32_e32 v173, v196, v196
	v_rcp_f32_e32 v174, v173
	v_mul_f32_e32 v156, v172, v58
	v_mul_f32_e32 v157, v172, v59
	v_mul_f32_e32 v158, v172, v60
	v_mul_f32_e32 v159, v172, v61
	v_mul_f32_e32 v160, v172, v54
	v_mul_f32_e32 v161, v172, v55
	v_mul_f32_e32 v162, v172, v56
	v_mul_f32_e32 v163, v172, v57
	v_exp_f32_e32 v156, v156
	v_exp_f32_e32 v157, v157
	v_exp_f32_e32 v158, v158
	v_exp_f32_e32 v159, v159
	v_exp_f32_e32 v160, v160
	v_exp_f32_e32 v161, v161
	v_exp_f32_e32 v162, v162
	v_exp_f32_e32 v163, v163
	v_mul_f32_e32 v62, v58, v62
	v_mul_f32_e32 v63, v59, v63
	v_mul_f32_e32 v64, v60, v64
	v_mul_f32_e32 v65, v61, v65
	v_mul_f32_e32 v50, v54, v50
	v_mul_f32_e32 v51, v55, v51
	v_mul_f32_e32 v52, v56, v52
	v_mul_f32_e32 v53, v57, v53
	v_fma_f32 v156, v156, v174, v174
	v_fma_f32 v157, v157, v174, v174
	v_fma_f32 v158, v158, v174, v174
	v_fma_f32 v159, v159, v174, v174
	v_fma_f32 v160, v160, v174, v174
	v_fma_f32 v161, v161, v174, v174
	v_fma_f32 v162, v162, v174, v174
	v_fma_f32 v163, v163, v174, v174
	v_rcp_f32_e32 v156, v156
	v_rcp_f32_e32 v157, v157
	v_rcp_f32_e32 v158, v158
	v_rcp_f32_e32 v159, v159
	v_rcp_f32_e32 v160, v160
	v_rcp_f32_e32 v161, v161
	v_rcp_f32_e32 v162, v162
	v_rcp_f32_e32 v163, v163
	s_add_u32 s26, s26, 0x6e000
	s_addc_u32 s27, s27, 0
	v_mul_f32_e32 v62, v62, v156
	v_mul_f32_e32 v63, v63, v157
	v_mul_f32_e32 v64, v64, v158
	v_mul_f32_e32 v65, v65, v159
	v_mul_f32_e32 v50, v50, v160
	v_mul_f32_e32 v51, v51, v161
	v_mul_f32_e32 v52, v52, v162
	v_mul_f32_e32 v53, v53, v163
	v_cvt_pk_bf16_f32 v58, v62, v63
	v_cvt_pk_bf16_f32 v59, v64, v65
	v_cvt_pk_bf16_f32 v60, v50, v51
	v_cvt_pk_bf16_f32 v61, v52, v53
	global_store_dwordx4 v175, v[58:61], s[26:27]
	s_waitcnt vmcnt(7)
	v_mul_f32_e32 v172, 0xbfb8aa3b, v198
	v_mul_f32_e32 v173, v198, v198
	v_rcp_f32_e32 v174, v173
	v_mul_f32_e32 v164, v172, v42
	v_mul_f32_e32 v165, v172, v43
	v_mul_f32_e32 v166, v172, v44
	v_mul_f32_e32 v167, v172, v45
	v_mul_f32_e32 v168, v172, v38
	v_mul_f32_e32 v169, v172, v39
	v_mul_f32_e32 v170, v172, v40
	v_mul_f32_e32 v171, v172, v41
	v_exp_f32_e32 v164, v164
	v_exp_f32_e32 v165, v165
	v_exp_f32_e32 v166, v166
	v_exp_f32_e32 v167, v167
	v_exp_f32_e32 v168, v168
	v_exp_f32_e32 v169, v169
	v_exp_f32_e32 v170, v170
	v_exp_f32_e32 v171, v171
	v_mul_f32_e32 v46, v42, v46
	v_mul_f32_e32 v47, v43, v47
	v_mul_f32_e32 v48, v44, v48
	v_mul_f32_e32 v49, v45, v49
	v_mul_f32_e32 v34, v38, v34
	v_mul_f32_e32 v35, v39, v35
	v_mul_f32_e32 v36, v40, v36
	v_mul_f32_e32 v37, v41, v37
	v_fma_f32 v164, v164, v174, v174
	v_fma_f32 v165, v165, v174, v174
	v_fma_f32 v166, v166, v174, v174
	v_fma_f32 v167, v167, v174, v174
	v_fma_f32 v168, v168, v174, v174
	v_fma_f32 v169, v169, v174, v174
	v_fma_f32 v170, v170, v174, v174
	v_fma_f32 v171, v171, v174, v174
	v_rcp_f32_e32 v164, v164
	v_rcp_f32_e32 v165, v165
	v_rcp_f32_e32 v166, v166
	v_rcp_f32_e32 v167, v167
	v_rcp_f32_e32 v168, v168
	v_rcp_f32_e32 v169, v169
	v_rcp_f32_e32 v170, v170
	v_rcp_f32_e32 v171, v171
	s_add_u32 s26, s26, 0x16000
	s_addc_u32 s27, s27, 0
	v_mul_f32_e32 v46, v46, v164
	v_mul_f32_e32 v47, v47, v165
	v_mul_f32_e32 v48, v48, v166
	v_mul_f32_e32 v49, v49, v167
	v_mul_f32_e32 v34, v34, v168
	v_mul_f32_e32 v35, v35, v169
	v_mul_f32_e32 v36, v36, v170
	v_mul_f32_e32 v37, v37, v171
	v_cvt_pk_bf16_f32 v42, v46, v47
	v_cvt_pk_bf16_f32 v43, v48, v49
	v_cvt_pk_bf16_f32 v44, v34, v35
	v_cvt_pk_bf16_f32 v45, v36, v37
	global_store_dwordx4 v175, v[42:45], s[26:27]
	s_waitcnt vmcnt(7)
	v_mul_f32_e32 v172, 0xbfb8aa3b, v200
	v_mul_f32_e32 v173, v200, v200
	v_rcp_f32_e32 v174, v173
	v_mul_f32_e32 v156, v172, v26
	v_mul_f32_e32 v157, v172, v27
	v_mul_f32_e32 v158, v172, v28
	v_mul_f32_e32 v159, v172, v29
	v_mul_f32_e32 v160, v172, v22
	v_mul_f32_e32 v161, v172, v23
	v_mul_f32_e32 v162, v172, v24
	v_mul_f32_e32 v163, v172, v25
	v_exp_f32_e32 v156, v156
	v_exp_f32_e32 v157, v157
	v_exp_f32_e32 v158, v158
	v_exp_f32_e32 v159, v159
	v_exp_f32_e32 v160, v160
	v_exp_f32_e32 v161, v161
	v_exp_f32_e32 v162, v162
	v_exp_f32_e32 v163, v163
	v_mul_f32_e32 v30, v26, v30
	v_mul_f32_e32 v31, v27, v31
	v_mul_f32_e32 v32, v28, v32
	v_mul_f32_e32 v33, v29, v33
	v_mul_f32_e32 v18, v22, v18
	v_mul_f32_e32 v19, v23, v19
	v_mul_f32_e32 v20, v24, v20
	v_mul_f32_e32 v21, v25, v21
	v_fma_f32 v156, v156, v174, v174
	v_fma_f32 v157, v157, v174, v174
	v_fma_f32 v158, v158, v174, v174
	v_fma_f32 v159, v159, v174, v174
	v_fma_f32 v160, v160, v174, v174
	v_fma_f32 v161, v161, v174, v174
	v_fma_f32 v162, v162, v174, v174
	v_fma_f32 v163, v163, v174, v174
	v_rcp_f32_e32 v156, v156
	v_rcp_f32_e32 v157, v157
	v_rcp_f32_e32 v158, v158
	v_rcp_f32_e32 v159, v159
	v_rcp_f32_e32 v160, v160
	v_rcp_f32_e32 v161, v161
	v_rcp_f32_e32 v162, v162
	v_rcp_f32_e32 v163, v163
	s_add_u32 s26, s26, 0x16000
	s_addc_u32 s27, s27, 0
	v_mul_f32_e32 v30, v30, v156
	v_mul_f32_e32 v31, v31, v157
	v_mul_f32_e32 v32, v32, v158
	v_mul_f32_e32 v33, v33, v159
	v_mul_f32_e32 v18, v18, v160
	v_mul_f32_e32 v19, v19, v161
	v_mul_f32_e32 v20, v20, v162
	v_mul_f32_e32 v21, v21, v163
	v_cvt_pk_bf16_f32 v26, v30, v31
	v_cvt_pk_bf16_f32 v27, v32, v33
	v_cvt_pk_bf16_f32 v28, v18, v19
	v_cvt_pk_bf16_f32 v29, v20, v21
	global_store_dwordx4 v175, v[26:29], s[26:27]
	s_waitcnt vmcnt(7)
	v_mul_f32_e32 v172, 0xbfb8aa3b, v202
	v_mul_f32_e32 v173, v202, v202
	v_rcp_f32_e32 v174, v173
	v_mul_f32_e32 v164, v172, v10
	v_mul_f32_e32 v165, v172, v11
	v_mul_f32_e32 v166, v172, v12
	v_mul_f32_e32 v167, v172, v13
	v_mul_f32_e32 v168, v172, v6
	v_mul_f32_e32 v169, v172, v7
	v_mul_f32_e32 v170, v172, v8
	v_mul_f32_e32 v171, v172, v9
	v_exp_f32_e32 v164, v164
	v_exp_f32_e32 v165, v165
	v_exp_f32_e32 v166, v166
	v_exp_f32_e32 v167, v167
	v_exp_f32_e32 v168, v168
	v_exp_f32_e32 v169, v169
	v_exp_f32_e32 v170, v170
	v_exp_f32_e32 v171, v171
	v_mul_f32_e32 v14, v10, v14
	v_mul_f32_e32 v15, v11, v15
	v_mul_f32_e32 v16, v12, v16
	v_mul_f32_e32 v17, v13, v17
	v_mul_f32_e32 v2, v6, v2
	v_mul_f32_e32 v3, v7, v3
	v_mul_f32_e32 v4, v8, v4
	v_mul_f32_e32 v5, v9, v5
	v_fma_f32 v164, v164, v174, v174
	v_fma_f32 v165, v165, v174, v174
	v_fma_f32 v166, v166, v174, v174
	v_fma_f32 v167, v167, v174, v174
	v_fma_f32 v168, v168, v174, v174
	v_fma_f32 v169, v169, v174, v174
	v_fma_f32 v170, v170, v174, v174
	v_fma_f32 v171, v171, v174, v174
	v_rcp_f32_e32 v164, v164
	v_rcp_f32_e32 v165, v165
	v_rcp_f32_e32 v166, v166
	v_rcp_f32_e32 v167, v167
	v_rcp_f32_e32 v168, v168
	v_rcp_f32_e32 v169, v169
	v_rcp_f32_e32 v170, v170
	v_rcp_f32_e32 v171, v171
	s_add_u32 s26, s26, 0x16000
	s_addc_u32 s27, s27, 0
	v_mul_f32_e32 v14, v14, v164
	v_mul_f32_e32 v15, v15, v165
	v_mul_f32_e32 v16, v16, v166
	v_mul_f32_e32 v17, v17, v167
	v_mul_f32_e32 v2, v2, v168
	v_mul_f32_e32 v3, v3, v169
	v_mul_f32_e32 v4, v4, v170
	v_mul_f32_e32 v5, v5, v171
	v_cvt_pk_bf16_f32 v10, v14, v15
	v_cvt_pk_bf16_f32 v11, v16, v17
	v_cvt_pk_bf16_f32 v12, v2, v3
	v_cvt_pk_bf16_f32 v13, v4, v5
	global_store_dwordx4 v175, v[10:13], s[26:27]
	s_cbranch_vccnz .LBB0_1554
	s_andn2_b64 vcc, exec, s[4:5]
	s_cbranch_vccnz .LBB0_1553
	s_barrier
	s_branch .LBB0_1553
